# baseline (speedup 1.0000x reference)
;     ...
;         for (int it = TIDX; it < 2 * (DFF / 8); it += 512) {
;           const int row = it / (DFF / 8), ck = it - row * (DFF / 8);
;           const int ch = ck * 8;
;           const int pg = (ch >> 7) * 256 + (ch & 127);
;           float res[8];
; #pragma unroll
;           for (int h = 0; h < 2; ++h) {
;             float cur[8], p1[8], p2[8], w0[8], w1[8], w2[8], bb[8];
;             const int pc = pg + h * 128, oc = ch + h * DFF;
;             ld8(UPB + ((size_t)pm * 4 + row) * UPW + pc, cur);
;             if (row == 1) { ld8(UPB + ((size_t)pm * 4 + 0) * UPW + pc, p1); ld8(UPB + ((size_t)(pm - 1) * 4 + 3) * UPW + pc, p2); }
;             else          { ld8(UPB + ((size_t)(pm - 1) * 4 + 3) * UPW + pc, p1); ld8(UPB + ((size_t)(pm - 1) * 4 + 2) * UPW + pc, p2); }
;             ld8f(p->w_conv + oc, w0); ld8f(p->w_conv + UPW + oc, w1); ld8f(p->w_conv + 2 * UPW + oc, w2); ld8f(p->b_conv + oc, bb);
.LBB0_543:
	v_mul_hi_i32 v2, v1, s40
	v_lshrrev_b32_e32 v3, 31, v2
	v_ashrrev_i32_e32 v2, 6, v2
	v_add_u32_e32 v8, v2, v3
	v_mad_i32_i24 v2, v8, s41, v1
	v_lshlrev_b32_e32 v6, 3, v2
	v_ashrrev_i32_e32 v9, 31, v8
	v_lshlrev_b32_e32 v2, 4, v2
	v_and_b32_e32 v3, 0x78, v6
	v_lshl_add_u64 v[4:5], s[18:19], 0, v[8:9]
	v_mov_b64_e32 v[12:13], s[12:13]
	v_and_or_b32 v2, v2, s43, v3
	v_mad_u64_u32 v[12:13], s[2:3], v4, s61, v[12:13]
	v_add_u32_e32 v3, 0xfffffea0, v1
	v_cmp_gt_u32_e64 s[2:3], s44, v3
	v_ashrrev_i32_e32 v3, 31, v2
	v_mad_i32_i24 v13, v5, s61, v13
	v_lshlrev_b64 v[14:15], 1, v[2:3]
	v_lshl_add_u64 v[16:17], v[12:13], 0, v[14:15]
	global_load_dwordx4 v[2:5], v[16:17], off
	global_load_dwordx4 v[152:155], v[16:17], off offset:256
	v_mov_b32_e32 v140, s28
	v_mov_b32_e32 v141, s35
	v_cndmask_b32_e64 v141, v140, v141, s[2:3]
	v_mov_b32_e32 v140, s26
	v_mov_b32_e32 v142, s29
	v_cndmask_b32_e64 v140, v140, v142, s[2:3]
	v_lshl_add_u64 v[164:165], v[140:141], 0, v[14:15]
	global_load_dwordx4 v[144:147], v[164:165], off
	global_load_dwordx4 v[156:159], v[164:165], off offset:256
	v_cndmask_b32_e64 v142, v203, v204, s[2:3]
	v_mov_b32_e32 v143, v0
	v_lshl_add_u64 v[166:167], s[36:37], 0, v[142:143]
	v_lshl_add_u64 v[166:167], v[166:167], 0, v[14:15]
	global_load_dwordx4 v[148:151], v[166:167], off
	global_load_dwordx4 v[160:163], v[166:167], off offset:256
	v_mov_b32_e32 v168, v6
	v_ashrrev_i32_e32 v169, 31, v6
	v_lshlrev_b64 v[168:169], 2, v[168:169]
	v_lshl_add_u64 v[170:171], s[6:7], 0, v[168:169]
	global_load_dwordx4 v[214:217], v[170:171], off offset:16
	global_load_dwordx4 v[218:221], v[170:171], off
	v_lshl_add_u64 v[172:173], v[170:171], 0, s[88:89]
	global_load_dwordx4 v[246:249], v[172:173], off
	global_load_dwordx4 v[250:253], v[172:173], off offset:16
	v_lshl_add_u64 v[170:171], s[4:5], 0, v[168:169]
	global_load_dwordx4 v[222:225], v[170:171], off offset:16
	global_load_dwordx4 v[226:229], v[170:171], off
	v_lshl_add_u64 v[172:173], v[170:171], 0, s[88:89]
	global_load_dwordx4 v[174:177], v[172:173], off
	global_load_dwordx4 v[178:181], v[172:173], off offset:16
	v_lshl_add_u64 v[170:171], s[20:21], 0, v[168:169]
	global_load_dwordx4 v[230:233], v[170:171], off offset:16
	global_load_dwordx4 v[234:237], v[170:171], off
	v_lshl_add_u64 v[172:173], v[170:171], 0, s[88:89]
	global_load_dwordx4 v[182:185], v[172:173], off
	global_load_dwordx4 v[186:189], v[172:173], off offset:16
	v_lshl_add_u64 v[170:171], s[22:23], 0, v[168:169]
	global_load_dwordx4 v[238:241], v[170:171], off offset:16
	global_load_dwordx4 v[242:245], v[170:171], off
	v_lshl_add_u64 v[172:173], v[170:171], 0, s[88:89]
	global_load_dwordx4 v[190:193], v[172:173], off
	global_load_dwordx4 v[194:197], v[172:173], off offset:16
	v_cndmask_b32_e64 v12, v203, v204, s[2:3]
	v_mov_b32_e32 v13, v0
	v_ashrrev_i32_e32 v7, 31, v6
	v_add_u32_e32 v8, s25, v8
	s_waitcnt vmcnt(0)
	v_lshlrev_b32_e32 v40, 16, v2
	v_and_b32_e32 v41, 0xffff0000, v2
	v_lshlrev_b32_e32 v72, 16, v3
	v_and_b32_e32 v73, 0xffff0000, v3
	v_mov_b32_e32 v2, s28
	v_mov_b32_e32 v3, s35
	v_lshlrev_b32_e32 v74, 16, v4
	v_and_b32_e32 v75, 0xffff0000, v4
	v_cndmask_b32_e64 v3, v2, v3, s[2:3]
	v_mov_b32_e32 v2, s26
	v_mov_b32_e32 v4, s29
	v_cndmask_b32_e64 v2, v2, v4, s[2:3]
	v_lshl_add_u64 v[18:19], v[2:3], 0, v[14:15]
	v_lshlrev_b32_e32 v76, 16, v5
	v_and_b32_e32 v77, 0xffff0000, v5
	v_mov_b32_e32 v2, v144
	v_mov_b32_e32 v3, v145
	v_mov_b32_e32 v4, v146
	v_mov_b32_e32 v5, v147
	s_waitcnt vmcnt(0)
	v_and_b32_e32 v79, 0xffff0000, v5
	v_lshlrev_b32_e32 v78, 16, v5
	v_and_b32_e32 v81, 0xffff0000, v4
	v_lshlrev_b32_e32 v80, 16, v4
	v_lshl_add_u64 v[4:5], s[36:37], 0, v[12:13]
	v_lshl_add_u64 v[20:21], v[4:5], 0, v[14:15]
	v_lshlrev_b64 v[4:5], 2, v[6:7]
	v_and_b32_e32 v83, 0xffff0000, v3
	v_lshlrev_b32_e32 v82, 16, v3
	v_and_b32_e32 v43, 0xffff0000, v2
	v_mov_b32_e32 v12, v148
	v_mov_b32_e32 v13, v149
	v_mov_b32_e32 v14, v150
	v_mov_b32_e32 v15, v151
	v_lshl_add_u64 v[48:49], s[4:5], 0, v[4:5]
	v_lshl_add_u64 v[56:57], s[20:21], 0, v[4:5]
	v_lshl_add_u64 v[64:65], s[22:23], 0, v[4:5]
	v_lshl_add_u64 v[46:47], s[6:7], 0, v[4:5]
	v_lshlrev_b32_e32 v42, 16, v2
	v_mov_b32_e32 v2, v152
	v_mov_b32_e32 v3, v153
	v_mov_b32_e32 v4, v154
	v_mov_b32_e32 v5, v155
	v_lshl_add_u64 v[50:51], v[46:47], 0, s[88:89]
	v_lshl_add_u64 v[52:53], v[48:49], 0, s[88:89]
	v_lshl_add_u64 v[60:61], v[56:57], 0, s[88:89]
	v_lshl_add_u64 v[68:69], v[64:65], 0, s[88:89]
	s_waitcnt vmcnt(1)
	v_and_b32_e32 v85, 0xffff0000, v15
	v_lshlrev_b32_e32 v84, 16, v15
	v_and_b32_e32 v87, 0xffff0000, v14
	v_lshlrev_b32_e32 v86, 16, v14
	v_and_b32_e32 v89, 0xffff0000, v13
	v_lshlrev_b32_e32 v88, 16, v13
	v_and_b32_e32 v45, 0xffff0000, v12
	v_lshlrev_b32_e32 v44, 16, v12
	s_waitcnt vmcnt(0)
	v_lshlrev_b32_e32 v90, 16, v2
	v_and_b32_e32 v91, 0xffff0000, v2
	v_lshlrev_b32_e32 v92, 16, v3
	v_and_b32_e32 v93, 0xffff0000, v3
	v_lshlrev_b32_e32 v94, 16, v4
	v_and_b32_e32 v95, 0xffff0000, v4
	v_lshlrev_b32_e32 v96, 16, v5
	v_and_b32_e32 v97, 0xffff0000, v5
	v_mov_b32_e32 v2, v156
	v_mov_b32_e32 v3, v157
	v_mov_b32_e32 v4, v158
	v_mov_b32_e32 v5, v159
	v_mov_b32_e32 v12, v160
	v_mov_b32_e32 v13, v161
	v_mov_b32_e32 v14, v162
	v_mov_b32_e32 v15, v163
	s_waitcnt vmcnt(1)
	v_and_b32_e32 v99, 0xffff0000, v5
	v_lshlrev_b32_e32 v98, 16, v5
	v_and_b32_e32 v101, 0xffff0000, v4
	v_lshlrev_b32_e32 v100, 16, v4
	v_and_b32_e32 v103, 0xffff0000, v3
	v_lshlrev_b32_e32 v102, 16, v3
	v_and_b32_e32 v105, 0xffff0000, v2
	s_waitcnt vmcnt(0)
; #define GAS __attribute__((address_space(1)))
;     ...
;             ld8(UPB + ((size_t)pm * 4 + row) * UPW + pc, cur);
;             if (row == 1) { ld8(UPB + ((size_t)pm * 4 + 0) * UPW + pc, p1); ld8(UPB + ((size_t)(pm - 1) * 4 + 3) * UPW + pc, p2); }
;             else          { ld8(UPB + ((size_t)(pm - 1) * 4 + 3) * UPW + pc, p1); ld8(UPB + ((size_t)(pm - 1) * 4 + 2) * UPW + pc, p2); }
;             ld8f(p->w_conv + oc, w0); ld8f(p->w_conv + UPW + oc, w1); ld8f(p->w_conv + 2 * UPW + oc, w2); ld8f(p->b_conv + oc, bb);
; #pragma unroll
;             for (int k = 0; k < 8; ++k) {
;               float cv = bb[k] + w0[k] * p2[k] + w1[k] * p1[k] + w2[k] * cur[k];
;               if (h == 0) res[k] = gelu_f(cv); else res[k] *= cv;
;             }
;           }
;           *(GAS uint4*)(FI + (size_t)(brow + row) * DFF + ch) =
;               make_uint4(pack2(res[0], res[1]), pack2(res[2], res[3]), pack2(res[4], res[5]), pack2(res[6], res[7]));
;         }
	v_and_b32_e32 v107, 0xffff0000, v15
	v_lshlrev_b32_e32 v106, 16, v15
	v_and_b32_e32 v109, 0xffff0000, v14
	v_lshlrev_b32_e32 v108, 16, v14
	v_and_b32_e32 v111, 0xffff0000, v13
	v_lshlrev_b32_e32 v110, 16, v13
	v_and_b32_e32 v113, 0xffff0000, v12
	v_lshlrev_b32_e32 v112, 16, v12
	v_lshlrev_b32_e32 v104, 16, v2
	v_mov_b32_e32 v2, v214
	v_mov_b32_e32 v3, v215
	v_mov_b32_e32 v4, v216
	v_mov_b32_e32 v5, v217
	v_mov_b32_e32 v12, v218
	v_mov_b32_e32 v13, v219
	v_mov_b32_e32 v14, v220
	v_mov_b32_e32 v15, v221
	v_mov_b32_e32 v16, v222
	v_mov_b32_e32 v17, v223
	v_mov_b32_e32 v18, v224
	v_mov_b32_e32 v19, v225
	v_mov_b32_e32 v20, v226
	v_mov_b32_e32 v21, v227
	v_mov_b32_e32 v22, v228
	v_mov_b32_e32 v23, v229
	v_mov_b32_e32 v24, v230
	v_mov_b32_e32 v25, v231
	v_mov_b32_e32 v26, v232
	v_mov_b32_e32 v27, v233
	v_mov_b32_e32 v28, v234
	v_mov_b32_e32 v29, v235
	v_mov_b32_e32 v30, v236
	v_mov_b32_e32 v31, v237
	v_mov_b32_e32 v32, v238
	v_mov_b32_e32 v33, v239
	v_mov_b32_e32 v34, v240
	v_mov_b32_e32 v35, v241
	v_mov_b32_e32 v36, v242
	v_mov_b32_e32 v37, v243
	v_mov_b32_e32 v38, v244
	v_mov_b32_e32 v39, v245
	s_waitcnt vmcnt(5)
	v_pk_fma_f32 v[2:3], v[16:17], v[86:87], v[2:3]
	s_waitcnt vmcnt(4)
	v_pk_fma_f32 v[12:13], v[20:21], v[44:45], v[12:13]
	v_pk_fma_f32 v[14:15], v[22:23], v[88:89], v[14:15]
	s_waitcnt vmcnt(2)
	v_pk_fma_f32 v[12:13], v[28:29], v[42:43], v[12:13]
	v_pk_fma_f32 v[14:15], v[30:31], v[82:83], v[14:15]
	s_waitcnt vmcnt(0)
	v_pk_fma_f32 v[12:13], v[36:37], v[40:41], v[12:13]
	v_pk_fma_f32 v[14:15], v[38:39], v[72:73], v[14:15]
	v_pk_mul_f32 v[20:21], v[12:13], v[12:13]
	v_pk_fma_f32 v[2:3], v[24:25], v[80:81], v[2:3]
	v_fmamk_f32 v9, v20, 0xbdd2d3e7, v198
	v_mul_f32_e32 v9, v12, v9
	v_exp_f32_e32 v9, v9
	v_pk_fma_f32 v[2:3], v[32:33], v[74:75], v[2:3]
	v_add_f32_e32 v9, 1.0, v9
	v_rcp_f32_e32 v20, v9
	v_fmamk_f32 v9, v21, 0xbdd2d3e7, v198
	v_mul_f32_e32 v9, v13, v9
	v_exp_f32_e32 v9, v9
	v_pk_mul_f32 v[16:17], v[2:3], v[2:3]
	v_add_f32_e32 v9, 1.0, v9
	v_rcp_f32_e32 v21, v9
	s_nop 0
	v_pk_mul_f32 v[12:13], v[12:13], v[20:21]
	v_add_co_u32_e64 v20, s[2:3], s80, v46
	s_nop 1
	v_addc_co_u32_e64 v21, s[2:3], 0, v47, s[2:3]
	v_mov_b32_e32 v40, v246
	v_mov_b32_e32 v41, v247
	v_mov_b32_e32 v42, v248
	v_mov_b32_e32 v43, v249
	v_mov_b32_e32 v44, v250
	v_mov_b32_e32 v45, v251
	v_mov_b32_e32 v46, v252
	v_mov_b32_e32 v47, v253
	v_add_co_u32_e64 v20, s[2:3], s80, v48
	s_nop 1
	v_addc_co_u32_e64 v21, s[2:3], 0, v49, s[2:3]
	v_mov_b32_e32 v48, v174
	v_mov_b32_e32 v49, v175
	v_mov_b32_e32 v50, v176
	v_mov_b32_e32 v51, v177
	s_nop 0
	v_mov_b32_e32 v52, v178
	v_mov_b32_e32 v53, v179
	v_mov_b32_e32 v54, v180
	v_mov_b32_e32 v55, v181
	v_add_co_u32_e64 v20, s[2:3], s80, v56
	s_nop 1
	v_addc_co_u32_e64 v21, s[2:3], 0, v57, s[2:3]
	v_mov_b32_e32 v56, v182
	v_mov_b32_e32 v57, v183
	v_mov_b32_e32 v58, v184
	v_mov_b32_e32 v59, v185
	s_nop 0
	v_mov_b32_e32 v60, v186
	v_mov_b32_e32 v61, v187
	v_mov_b32_e32 v62, v188
	v_mov_b32_e32 v63, v189
	v_add_co_u32_e64 v20, s[2:3], s80, v64
	s_nop 1
	v_addc_co_u32_e64 v21, s[2:3], 0, v65, s[2:3]
	v_mov_b32_e32 v64, v190
	v_mov_b32_e32 v65, v191
	v_mov_b32_e32 v66, v192
	v_mov_b32_e32 v67, v193
	s_nop 0
	v_mov_b32_e32 v68, v194
	v_mov_b32_e32 v69, v195
	v_mov_b32_e32 v70, v196
	v_mov_b32_e32 v71, v197
	s_waitcnt vmcnt(5)
	v_pk_fma_f32 v[20:21], v[48:49], v[112:113], v[40:41]
	s_waitcnt vmcnt(3)
	v_pk_fma_f32 v[20:21], v[56:57], v[104:105], v[20:21]
	s_waitcnt vmcnt(1)
	v_pk_fma_f32 v[20:21], v[64:65], v[90:91], v[20:21]
	s_nop 0
	v_pk_mul_f32 v[12:13], v[12:13], v[20:21]
	v_pk_mul_f32 v[20:21], v[14:15], v[14:15]
	s_nop 0
	v_fmamk_f32 v9, v20, 0xbdd2d3e7, v198
	v_mul_f32_e32 v9, v14, v9
	v_exp_f32_e32 v9, v9
	s_nop 0
	v_add_f32_e32 v9, 1.0, v9
	v_rcp_f32_e32 v20, v9
	v_fmamk_f32 v9, v21, 0xbdd2d3e7, v198
	v_mul_f32_e32 v9, v15, v9
	v_exp_f32_e32 v9, v9
	s_nop 0
	v_add_f32_e32 v9, 1.0, v9
	v_rcp_f32_e32 v21, v9
	v_fmamk_f32 v9, v16, 0xbdd2d3e7, v198
	v_mul_f32_e32 v9, v2, v9
	v_exp_f32_e32 v9, v9
	v_pk_mul_f32 v[14:15], v[14:15], v[20:21]
	v_pk_fma_f32 v[20:21], v[50:51], v[110:111], v[42:43]
	v_add_f32_e32 v9, 1.0, v9
	v_rcp_f32_e32 v16, v9
	v_fmamk_f32 v9, v17, 0xbdd2d3e7, v198
	v_mul_f32_e32 v9, v3, v9
	v_exp_f32_e32 v9, v9
	v_pk_fma_f32 v[20:21], v[58:59], v[102:103], v[20:21]
	v_add_f32_e32 v9, 1.0, v9
	v_rcp_f32_e32 v17, v9
	v_pk_fma_f32 v[20:21], v[66:67], v[92:93], v[20:21]
	v_pk_mul_f32 v[2:3], v[2:3], v[16:17]
	v_pk_fma_f32 v[16:17], v[52:53], v[108:109], v[44:45]
	v_pk_mul_f32 v[14:15], v[14:15], v[20:21]
	v_pk_fma_f32 v[16:17], v[60:61], v[100:101], v[16:17]
	s_waitcnt vmcnt(0)
	v_pk_fma_f32 v[16:17], v[68:69], v[94:95], v[16:17]
	s_nop 0
	v_pk_mul_f32 v[16:17], v[2:3], v[16:17]
	v_pk_fma_f32 v[2:3], v[18:19], v[84:85], v[4:5]
	s_nop 0
	v_pk_fma_f32 v[2:3], v[26:27], v[78:79], v[2:3]
	s_nop 0
	v_pk_fma_f32 v[2:3], v[34:35], v[76:77], v[2:3]
	s_nop 0
	v_pk_mul_f32 v[4:5], v[2:3], v[2:3]
	s_nop 0
	v_fmamk_f32 v4, v4, 0xbdd2d3e7, v198
	v_fmamk_f32 v5, v5, 0xbdd2d3e7, v198
	v_mul_f32_e32 v4, v2, v4
	v_mul_f32_e32 v5, v3, v5
	v_exp_f32_e32 v4, v4
	v_exp_f32_e32 v5, v5
	v_add_f32_e32 v4, 1.0, v4
	v_add_f32_e32 v5, 1.0, v5
	v_rcp_f32_e32 v4, v4
	v_rcp_f32_e32 v5, v5
	s_nop 0
	v_pk_mul_f32 v[2:3], v[2:3], v[4:5]
	v_pk_fma_f32 v[4:5], v[54:55], v[106:107], v[46:47]
	s_nop 0
	v_pk_fma_f32 v[4:5], v[62:63], v[98:99], v[4:5]
	s_nop 0
	v_pk_fma_f32 v[4:5], v[70:71], v[96:97], v[4:5]
	s_nop 0
	v_pk_mul_f32 v[18:19], v[2:3], v[4:5]
	v_cvt_pk_bf16_f32 v2, v12, v13
	v_mov_b64_e32 v[12:13], s[14:15]
	v_mad_i64_i32 v[8:9], s[2:3], v8, s63, v[12:13]
	v_cmp_lt_i32_e64 s[2:3], s45, v1
	v_cvt_pk_bf16_f32 v3, v14, v15
	v_cvt_pk_bf16_f32 v4, v16, v17
	v_cvt_pk_bf16_f32 v5, v18, v19
	v_lshl_add_u64 v[6:7], v[6:7], 1, v[8:9]
	v_add_u32_e32 v1, 0x200, v1
	s_or_b64 s[38:39], s[2:3], s[38:39]
	global_store_dwordx4 v[6:7], v[2:5], off
	s_andn2_b64 exec, exec, s[38:39]
	s_cbranch_execnz .LBB0_543
	s_branch .LBB0_536

;     ...
;         for (int it = TIDX; it < 2 * (DFF / 8); it += 512) {
;           const int row = it / (DFF / 8), ck = it - row * (DFF / 8);
;           const int ch = ck * 8;
;           const int pg = (ch >> 7) * 256 + (ch & 127);
;           float res[8];
; #pragma unroll
;           for (int h = 0; h < 2; ++h) {
;             float cur[8], p1[8], p2[8], w0[8], w1[8], w2[8], bb[8];
;             const int pc = pg + h * 128, oc = ch + h * DFF;
;             ld8(UPB + ((size_t)pm * 4 + row) * UPW + pc, cur);
;             if (row == 1) { ld8(UPB + ((size_t)pm * 4 + 0) * UPW + pc, p1); ld8(UPB + ((size_t)(pm - 1) * 4 + 3) * UPW + pc, p2); }
;             else          { ld8(UPB + ((size_t)(pm - 1) * 4 + 3) * UPW + pc, p1); ld8(UPB + ((size_t)(pm - 1) * 4 + 2) * UPW + pc, p2); }
;             ld8f(p->w_conv + oc, w0); ld8f(p->w_conv + UPW + oc, w1); ld8f(p->w_conv + 2 * UPW + oc, w2); ld8f(p->b_conv + oc, bb);
.LBB0_927:
	v_mul_hi_i32 v2, v1, s42
	v_lshrrev_b32_e32 v3, 31, v2
	v_ashrrev_i32_e32 v2, 6, v2
	v_add_u32_e32 v8, v2, v3
	v_mad_i32_i24 v2, v8, s44, v1
	v_lshlrev_b32_e32 v6, 3, v2
	v_ashrrev_i32_e32 v9, 31, v8
	v_lshlrev_b32_e32 v2, 4, v2
	v_and_b32_e32 v3, 0x78, v6
	v_lshl_add_u64 v[4:5], s[18:19], 0, v[8:9]
	v_mov_b64_e32 v[12:13], s[12:13]
	v_and_or_b32 v2, v2, s45, v3
	v_mad_u64_u32 v[12:13], s[2:3], v4, s61, v[12:13]
	v_add_u32_e32 v3, 0xfffffea0, v1
	v_cmp_gt_u32_e64 s[2:3], s48, v3
	v_ashrrev_i32_e32 v3, 31, v2
	v_mad_i32_i24 v13, v5, s61, v13
	v_lshlrev_b64 v[14:15], 1, v[2:3]
	v_lshl_add_u64 v[16:17], v[12:13], 0, v[14:15]
	global_load_dwordx4 v[2:5], v[16:17], off
	global_load_dwordx4 v[152:155], v[16:17], off offset:256
	v_mov_b32_e32 v140, s28
	v_mov_b32_e32 v141, s38
	v_cndmask_b32_e64 v141, v140, v141, s[2:3]
	v_mov_b32_e32 v140, s27
	v_mov_b32_e32 v142, s29
	v_cndmask_b32_e64 v140, v140, v142, s[2:3]
	v_lshl_add_u64 v[164:165], v[140:141], 0, v[14:15]
	global_load_dwordx4 v[144:147], v[164:165], off
	global_load_dwordx4 v[156:159], v[164:165], off offset:256
	v_cndmask_b32_e64 v142, v203, v204, s[2:3]
	v_mov_b32_e32 v143, v0
	v_lshl_add_u64 v[166:167], s[36:37], 0, v[142:143]
	v_lshl_add_u64 v[166:167], v[166:167], 0, v[14:15]
	global_load_dwordx4 v[148:151], v[166:167], off
	global_load_dwordx4 v[160:163], v[166:167], off offset:256
	v_mov_b32_e32 v168, v6
	v_ashrrev_i32_e32 v169, 31, v6
	v_lshlrev_b64 v[168:169], 2, v[168:169]
	v_lshl_add_u64 v[170:171], s[6:7], 0, v[168:169]
	global_load_dwordx4 v[214:217], v[170:171], off offset:16
	global_load_dwordx4 v[218:221], v[170:171], off
	v_lshl_add_u64 v[172:173], v[170:171], 0, s[88:89]
	global_load_dwordx4 v[246:249], v[172:173], off
	global_load_dwordx4 v[250:253], v[172:173], off offset:16
	v_lshl_add_u64 v[170:171], s[4:5], 0, v[168:169]
	global_load_dwordx4 v[222:225], v[170:171], off offset:16
	global_load_dwordx4 v[226:229], v[170:171], off
	v_lshl_add_u64 v[172:173], v[170:171], 0, s[88:89]
	global_load_dwordx4 v[174:177], v[172:173], off
	global_load_dwordx4 v[178:181], v[172:173], off offset:16
	v_lshl_add_u64 v[170:171], s[20:21], 0, v[168:169]
	global_load_dwordx4 v[230:233], v[170:171], off offset:16
	global_load_dwordx4 v[234:237], v[170:171], off
	v_lshl_add_u64 v[172:173], v[170:171], 0, s[88:89]
	global_load_dwordx4 v[182:185], v[172:173], off
	global_load_dwordx4 v[186:189], v[172:173], off offset:16
	v_lshl_add_u64 v[170:171], s[22:23], 0, v[168:169]
	global_load_dwordx4 v[238:241], v[170:171], off offset:16
	global_load_dwordx4 v[242:245], v[170:171], off
	v_lshl_add_u64 v[172:173], v[170:171], 0, s[88:89]
	global_load_dwordx4 v[190:193], v[172:173], off
	global_load_dwordx4 v[194:197], v[172:173], off offset:16
	v_cndmask_b32_e64 v12, v203, v204, s[2:3]
	v_mov_b32_e32 v13, v0
	v_ashrrev_i32_e32 v7, 31, v6
	v_add_u32_e32 v8, s26, v8
	s_waitcnt vmcnt(0)
	v_lshlrev_b32_e32 v40, 16, v2
	v_and_b32_e32 v41, 0xffff0000, v2
	v_lshlrev_b32_e32 v72, 16, v3
	v_and_b32_e32 v73, 0xffff0000, v3
	v_mov_b32_e32 v2, s28
	v_mov_b32_e32 v3, s38
	v_lshlrev_b32_e32 v74, 16, v4
	v_and_b32_e32 v75, 0xffff0000, v4
	v_cndmask_b32_e64 v3, v2, v3, s[2:3]
	v_mov_b32_e32 v2, s27
	v_mov_b32_e32 v4, s29
	v_cndmask_b32_e64 v2, v2, v4, s[2:3]
	v_lshl_add_u64 v[18:19], v[2:3], 0, v[14:15]
	v_lshlrev_b32_e32 v76, 16, v5
	v_and_b32_e32 v77, 0xffff0000, v5
	v_mov_b32_e32 v2, v144
	v_mov_b32_e32 v3, v145
	v_mov_b32_e32 v4, v146
	v_mov_b32_e32 v5, v147
	s_waitcnt vmcnt(0)
	v_and_b32_e32 v79, 0xffff0000, v5
	v_lshlrev_b32_e32 v78, 16, v5
	v_and_b32_e32 v81, 0xffff0000, v4
	v_lshlrev_b32_e32 v80, 16, v4
	v_lshl_add_u64 v[4:5], s[36:37], 0, v[12:13]
	v_lshl_add_u64 v[20:21], v[4:5], 0, v[14:15]
	v_lshlrev_b64 v[4:5], 2, v[6:7]
	v_and_b32_e32 v83, 0xffff0000, v3
	v_lshlrev_b32_e32 v82, 16, v3
	v_and_b32_e32 v43, 0xffff0000, v2
	v_mov_b32_e32 v12, v148
	v_mov_b32_e32 v13, v149
	v_mov_b32_e32 v14, v150
	v_mov_b32_e32 v15, v151
	v_lshl_add_u64 v[48:49], s[4:5], 0, v[4:5]
	v_lshl_add_u64 v[56:57], s[20:21], 0, v[4:5]
	v_lshl_add_u64 v[64:65], s[22:23], 0, v[4:5]
	v_lshl_add_u64 v[46:47], s[6:7], 0, v[4:5]
	v_lshlrev_b32_e32 v42, 16, v2
	v_mov_b32_e32 v2, v152
	v_mov_b32_e32 v3, v153
	v_mov_b32_e32 v4, v154
	v_mov_b32_e32 v5, v155
	v_lshl_add_u64 v[50:51], v[46:47], 0, s[88:89]
	v_lshl_add_u64 v[52:53], v[48:49], 0, s[88:89]
	v_lshl_add_u64 v[60:61], v[56:57], 0, s[88:89]
	v_lshl_add_u64 v[68:69], v[64:65], 0, s[88:89]
	s_waitcnt vmcnt(1)
	v_and_b32_e32 v85, 0xffff0000, v15
	v_lshlrev_b32_e32 v84, 16, v15
	v_and_b32_e32 v87, 0xffff0000, v14
	v_lshlrev_b32_e32 v86, 16, v14
	v_and_b32_e32 v89, 0xffff0000, v13
	v_lshlrev_b32_e32 v88, 16, v13
	v_and_b32_e32 v45, 0xffff0000, v12
	v_lshlrev_b32_e32 v44, 16, v12
	s_waitcnt vmcnt(0)
	v_lshlrev_b32_e32 v90, 16, v2
	v_and_b32_e32 v91, 0xffff0000, v2
	v_lshlrev_b32_e32 v92, 16, v3
	v_and_b32_e32 v93, 0xffff0000, v3
	v_lshlrev_b32_e32 v94, 16, v4
	v_and_b32_e32 v95, 0xffff0000, v4
	v_lshlrev_b32_e32 v96, 16, v5
	v_and_b32_e32 v97, 0xffff0000, v5
	v_mov_b32_e32 v2, v156
	v_mov_b32_e32 v3, v157
	v_mov_b32_e32 v4, v158
	v_mov_b32_e32 v5, v159
	v_mov_b32_e32 v12, v160
	v_mov_b32_e32 v13, v161
	v_mov_b32_e32 v14, v162
	v_mov_b32_e32 v15, v163
	s_waitcnt vmcnt(1)
	v_and_b32_e32 v99, 0xffff0000, v5
	v_lshlrev_b32_e32 v98, 16, v5
	v_and_b32_e32 v101, 0xffff0000, v4
	v_lshlrev_b32_e32 v100, 16, v4
	v_and_b32_e32 v103, 0xffff0000, v3
	v_lshlrev_b32_e32 v102, 16, v3
	v_and_b32_e32 v105, 0xffff0000, v2
	s_waitcnt vmcnt(0)
; #define GAS __attribute__((address_space(1)))
;     ...
;             ld8(UPB + ((size_t)pm * 4 + row) * UPW + pc, cur);
;             if (row == 1) { ld8(UPB + ((size_t)pm * 4 + 0) * UPW + pc, p1); ld8(UPB + ((size_t)(pm - 1) * 4 + 3) * UPW + pc, p2); }
;             else          { ld8(UPB + ((size_t)(pm - 1) * 4 + 3) * UPW + pc, p1); ld8(UPB + ((size_t)(pm - 1) * 4 + 2) * UPW + pc, p2); }
;             ld8f(p->w_conv + oc, w0); ld8f(p->w_conv + UPW + oc, w1); ld8f(p->w_conv + 2 * UPW + oc, w2); ld8f(p->b_conv + oc, bb);
; #pragma unroll
;             for (int k = 0; k < 8; ++k) {
;               float cv = bb[k] + w0[k] * p2[k] + w1[k] * p1[k] + w2[k] * cur[k];
;               if (h == 0) res[k] = gelu_f(cv); else res[k] *= cv;
;             }
;           }
;           *(GAS uint4*)(FI + (size_t)(brow + row) * DFF + ch) =
;               make_uint4(pack2(res[0], res[1]), pack2(res[2], res[3]), pack2(res[4], res[5]), pack2(res[6], res[7]));
;         }
	v_and_b32_e32 v107, 0xffff0000, v15
	v_lshlrev_b32_e32 v106, 16, v15
	v_and_b32_e32 v109, 0xffff0000, v14
	v_lshlrev_b32_e32 v108, 16, v14
	v_and_b32_e32 v111, 0xffff0000, v13
	v_lshlrev_b32_e32 v110, 16, v13
	v_and_b32_e32 v113, 0xffff0000, v12
	v_lshlrev_b32_e32 v112, 16, v12
	v_lshlrev_b32_e32 v104, 16, v2
	v_mov_b32_e32 v2, v214
	v_mov_b32_e32 v3, v215
	v_mov_b32_e32 v4, v216
	v_mov_b32_e32 v5, v217
	v_mov_b32_e32 v12, v218
	v_mov_b32_e32 v13, v219
	v_mov_b32_e32 v14, v220
	v_mov_b32_e32 v15, v221
	v_mov_b32_e32 v16, v222
	v_mov_b32_e32 v17, v223
	v_mov_b32_e32 v18, v224
	v_mov_b32_e32 v19, v225
	v_mov_b32_e32 v20, v226
	v_mov_b32_e32 v21, v227
	v_mov_b32_e32 v22, v228
	v_mov_b32_e32 v23, v229
	v_mov_b32_e32 v24, v230
	v_mov_b32_e32 v25, v231
	v_mov_b32_e32 v26, v232
	v_mov_b32_e32 v27, v233
	v_mov_b32_e32 v28, v234
	v_mov_b32_e32 v29, v235
	v_mov_b32_e32 v30, v236
	v_mov_b32_e32 v31, v237
	v_mov_b32_e32 v32, v238
	v_mov_b32_e32 v33, v239
	v_mov_b32_e32 v34, v240
	v_mov_b32_e32 v35, v241
	v_mov_b32_e32 v36, v242
	v_mov_b32_e32 v37, v243
	v_mov_b32_e32 v38, v244
	v_mov_b32_e32 v39, v245
	s_waitcnt vmcnt(5)
	v_pk_fma_f32 v[2:3], v[16:17], v[86:87], v[2:3]
	s_waitcnt vmcnt(4)
	v_pk_fma_f32 v[12:13], v[20:21], v[44:45], v[12:13]
	v_pk_fma_f32 v[14:15], v[22:23], v[88:89], v[14:15]
	s_waitcnt vmcnt(2)
	v_pk_fma_f32 v[12:13], v[28:29], v[42:43], v[12:13]
	v_pk_fma_f32 v[14:15], v[30:31], v[82:83], v[14:15]
	s_waitcnt vmcnt(0)
	v_pk_fma_f32 v[12:13], v[36:37], v[40:41], v[12:13]
	v_pk_fma_f32 v[14:15], v[38:39], v[72:73], v[14:15]
	v_pk_mul_f32 v[20:21], v[12:13], v[12:13]
	v_pk_fma_f32 v[2:3], v[24:25], v[80:81], v[2:3]
	v_fmamk_f32 v9, v20, 0xbdd2d3e7, v198
	v_mul_f32_e32 v9, v12, v9
	v_exp_f32_e32 v9, v9
	v_pk_fma_f32 v[2:3], v[32:33], v[74:75], v[2:3]
	v_add_f32_e32 v9, 1.0, v9
	v_rcp_f32_e32 v20, v9
	v_fmamk_f32 v9, v21, 0xbdd2d3e7, v198
	v_mul_f32_e32 v9, v13, v9
	v_exp_f32_e32 v9, v9
	v_pk_mul_f32 v[16:17], v[2:3], v[2:3]
	v_add_f32_e32 v9, 1.0, v9
	v_rcp_f32_e32 v21, v9
	s_nop 0
	v_pk_mul_f32 v[12:13], v[12:13], v[20:21]
	v_add_co_u32_e64 v20, s[2:3], s80, v46
	s_nop 1
	v_addc_co_u32_e64 v21, s[2:3], 0, v47, s[2:3]
	v_mov_b32_e32 v40, v246
	v_mov_b32_e32 v41, v247
	v_mov_b32_e32 v42, v248
	v_mov_b32_e32 v43, v249
	v_mov_b32_e32 v44, v250
	v_mov_b32_e32 v45, v251
	v_mov_b32_e32 v46, v252
	v_mov_b32_e32 v47, v253
	v_add_co_u32_e64 v20, s[2:3], s80, v48
	s_nop 1
	v_addc_co_u32_e64 v21, s[2:3], 0, v49, s[2:3]
	v_mov_b32_e32 v48, v174
	v_mov_b32_e32 v49, v175
	v_mov_b32_e32 v50, v176
	v_mov_b32_e32 v51, v177
	s_nop 0
	v_mov_b32_e32 v52, v178
	v_mov_b32_e32 v53, v179
	v_mov_b32_e32 v54, v180
	v_mov_b32_e32 v55, v181
	v_add_co_u32_e64 v20, s[2:3], s80, v56
	s_nop 1
	v_addc_co_u32_e64 v21, s[2:3], 0, v57, s[2:3]
	v_mov_b32_e32 v56, v182
	v_mov_b32_e32 v57, v183
	v_mov_b32_e32 v58, v184
	v_mov_b32_e32 v59, v185
	s_nop 0
	v_mov_b32_e32 v60, v186
	v_mov_b32_e32 v61, v187
	v_mov_b32_e32 v62, v188
	v_mov_b32_e32 v63, v189
	v_add_co_u32_e64 v20, s[2:3], s80, v64
	s_nop 1
	v_addc_co_u32_e64 v21, s[2:3], 0, v65, s[2:3]
	v_mov_b32_e32 v64, v190
	v_mov_b32_e32 v65, v191
	v_mov_b32_e32 v66, v192
	v_mov_b32_e32 v67, v193
	s_nop 0
	v_mov_b32_e32 v68, v194
	v_mov_b32_e32 v69, v195
	v_mov_b32_e32 v70, v196
	v_mov_b32_e32 v71, v197
	s_waitcnt vmcnt(5)
	v_pk_fma_f32 v[20:21], v[48:49], v[112:113], v[40:41]
	s_waitcnt vmcnt(3)
	v_pk_fma_f32 v[20:21], v[56:57], v[104:105], v[20:21]
	s_waitcnt vmcnt(1)
	v_pk_fma_f32 v[20:21], v[64:65], v[90:91], v[20:21]
	s_nop 0
	v_pk_mul_f32 v[12:13], v[12:13], v[20:21]
	v_pk_mul_f32 v[20:21], v[14:15], v[14:15]
	s_nop 0
	v_fmamk_f32 v9, v20, 0xbdd2d3e7, v198
	v_mul_f32_e32 v9, v14, v9
	v_exp_f32_e32 v9, v9
	s_nop 0
	v_add_f32_e32 v9, 1.0, v9
	v_rcp_f32_e32 v20, v9
	v_fmamk_f32 v9, v21, 0xbdd2d3e7, v198
	v_mul_f32_e32 v9, v15, v9
	v_exp_f32_e32 v9, v9
	s_nop 0
	v_add_f32_e32 v9, 1.0, v9
	v_rcp_f32_e32 v21, v9
	v_fmamk_f32 v9, v16, 0xbdd2d3e7, v198
	v_mul_f32_e32 v9, v2, v9
	v_exp_f32_e32 v9, v9
	v_pk_mul_f32 v[14:15], v[14:15], v[20:21]
	v_pk_fma_f32 v[20:21], v[50:51], v[110:111], v[42:43]
	v_add_f32_e32 v9, 1.0, v9
	v_rcp_f32_e32 v16, v9
	v_fmamk_f32 v9, v17, 0xbdd2d3e7, v198
	v_mul_f32_e32 v9, v3, v9
	v_exp_f32_e32 v9, v9
	v_pk_fma_f32 v[20:21], v[58:59], v[102:103], v[20:21]
	v_add_f32_e32 v9, 1.0, v9
	v_rcp_f32_e32 v17, v9
	v_pk_fma_f32 v[20:21], v[66:67], v[92:93], v[20:21]
	v_pk_mul_f32 v[2:3], v[2:3], v[16:17]
	v_pk_fma_f32 v[16:17], v[52:53], v[108:109], v[44:45]
	v_pk_mul_f32 v[14:15], v[14:15], v[20:21]
	v_pk_fma_f32 v[16:17], v[60:61], v[100:101], v[16:17]
	s_waitcnt vmcnt(0)
	v_pk_fma_f32 v[16:17], v[68:69], v[94:95], v[16:17]
	s_nop 0
	v_pk_mul_f32 v[16:17], v[2:3], v[16:17]
	v_pk_fma_f32 v[2:3], v[18:19], v[84:85], v[4:5]
	s_nop 0
	v_pk_fma_f32 v[2:3], v[26:27], v[78:79], v[2:3]
	s_nop 0
	v_pk_fma_f32 v[2:3], v[34:35], v[76:77], v[2:3]
	s_nop 0
	v_pk_mul_f32 v[4:5], v[2:3], v[2:3]
	s_nop 0
	v_fmamk_f32 v4, v4, 0xbdd2d3e7, v198
	v_fmamk_f32 v5, v5, 0xbdd2d3e7, v198
	v_mul_f32_e32 v4, v2, v4
	v_mul_f32_e32 v5, v3, v5
	v_exp_f32_e32 v4, v4
	v_exp_f32_e32 v5, v5
	v_add_f32_e32 v4, 1.0, v4
	v_add_f32_e32 v5, 1.0, v5
	v_rcp_f32_e32 v4, v4
	v_rcp_f32_e32 v5, v5
	s_nop 0
	v_pk_mul_f32 v[2:3], v[2:3], v[4:5]
	v_pk_fma_f32 v[4:5], v[54:55], v[106:107], v[46:47]
	s_nop 0
	v_pk_fma_f32 v[4:5], v[62:63], v[98:99], v[4:5]
	s_nop 0
	v_pk_fma_f32 v[4:5], v[70:71], v[96:97], v[4:5]
	s_nop 0
	v_pk_mul_f32 v[18:19], v[2:3], v[4:5]
	v_cvt_pk_bf16_f32 v2, v12, v13
	v_mov_b64_e32 v[12:13], s[14:15]
	v_mad_i64_i32 v[8:9], s[2:3], v8, s63, v[12:13]
	v_cmp_lt_i32_e64 s[2:3], s49, v1
	v_cvt_pk_bf16_f32 v3, v14, v15
	v_cvt_pk_bf16_f32 v4, v16, v17
	v_cvt_pk_bf16_f32 v5, v18, v19
	v_lshl_add_u64 v[6:7], v[6:7], 1, v[8:9]
	v_add_u32_e32 v1, 0x200, v1
	s_or_b64 s[40:41], s[2:3], s[40:41]
	global_store_dwordx4 v[6:7], v[2:5], off
	s_andn2_b64 exec, exec, s[40:41]
	s_cbranch_execnz .LBB0_927
	s_branch .LBB0_920
